# E2 sample attention as an 8-wave workgroup task on f32 MFMA (v_mfma_f32_16x16x4_f32), K/V rows requested up front
# speedup vs baseline: 1.1082x; 1.0045x over previous
; #define LAS __attribute__((address_space(3)))
; __device__ __forceinline__ float bf1(bf16_t h) { return __uint_as_float((unsigned)h << 16); }
; __device__ __forceinline__ void attn_sample_item(LAS float* wl, const bf16_t* z, bf16_t* mix, const float* sinks, const float* ck, const float* cv, int it, int lane) {
;     const int h = it & 15, b = it >> 4, kv = h >> 3;
;     LAS float* qs = wl;
;     LAS float* pT = wl + 512;
;     const size_t tok0 = (size_t)T_P + b * 8;
; #pragma unroll
;     for (int t = 0; t < 8; ++t) qs[t * 64 + lane] = bf1(z[(tok0 + t) * EIN + h * 64 + lane]);
;     __builtin_amdgcn_wave_barrier();
;     asm volatile("s_waitcnt lgkmcnt(0)" ::: "memory");
;     const float slope = exp2f(-0.5f * (float)(h + 1)), sink = sinks[h];
;     float s[3][8];
; #pragma unroll
;     for (int ps = 0; ps < 3; ++ps) {
;         const int idx = lane + 64 * ps;
; #pragma unroll
;         for (int t = 0; t < 8; ++t) s[ps][t] = 0.f;
;         if (idx < 128) {
;             const f32x4* kp = (const f32x4*)(ck + (((size_t)b * 128 + idx) * 2 + kv) * 64);
; #pragma unroll 8
;             for (int d4 = 0; d4 < 16; ++d4) {
;                 const f32x4 k4 = kp[d4];
; #pragma unroll
;                 for (int t = 0; t < 8; ++t) { const f32x4 q4 = *(const LAS f32x4*)(qs + t * 64 + 4 * d4); s[ps][t] += (k4[0] * q4[0] + k4[1] * q4[1]) + (k4[2] * q4[2] + k4[3] * q4[3]); }
;             }
;         } else if (idx < 136) {
;             const bf16_t* kp = z + (tok0 + (idx - 128)) * EIN + 1024 + kv * 64;
; #pragma unroll 4
; __global__ void __launch_bounds__(NTHREADS, 2) hybrid_fwd(Params P) {
;     ...
;                 if (PHS(14)) for (int it = gw; it < 2048; it += NGW) if ((it & 3) == 0) attn_sample_item(wl, Z, MIX, sinks, ck, cv, it >> 2, lane);
.LBB0_1059:
.LBB0_1060:
	v_readlane_b32 s4, v254, 50
	v_readlane_b32 s5, v254, 51
	s_lshl_b64 s[42:43], s[4:5], 21
	s_cmpk_gt_i32 s54, 0x7ff
	s_cbranch_scc1 .LBB0_1095
	v_sub_u32_e32 v0, 0x80, v82
	v_cvt_f32_ubyte0_e32 v59, v0
	v_sub_u32_e32 v0, 0x81, v82
	v_cvt_f32_ubyte0_e32 v60, v0
	v_sub_u32_e32 v0, 0x82, v82
	v_cvt_f32_ubyte0_e32 v61, v0
	v_sub_u32_e32 v0, 0x83, v82
	v_cvt_f32_ubyte0_e32 v62, v0
	v_sub_u32_e32 v0, 0x84, v82
	v_cvt_f32_ubyte0_e32 v63, v0
	v_sub_u32_e32 v0, 0x85, v82
	v_cvt_f32_ubyte0_e32 v64, v0
	v_sub_u32_e32 v0, 0x86, v82
	v_cvt_f32_ubyte0_e32 v65, v0
	v_sub_u32_e32 v0, 0x87, v82
	v_cvt_f32_ubyte0_e32 v66, v0
	v_or_b32_e32 v0, 64, v82
	v_sub_u32_e32 v2, 0x80, v0
	v_cvt_f32_ubyte0_e32 v67, v2
	v_sub_u32_e32 v2, 0x81, v0
	v_cvt_f32_ubyte0_e32 v68, v2
	v_sub_u32_e32 v2, 0x82, v0
	v_cvt_f32_ubyte0_e32 v69, v2
	v_sub_u32_e32 v2, 0x83, v0
	v_cvt_f32_ubyte0_e32 v70, v2
	v_sub_u32_e32 v2, 0x84, v0
	v_cvt_f32_ubyte0_e32 v71, v2
	v_sub_u32_e32 v2, 0x85, v0
	v_cvt_f32_ubyte0_e32 v72, v2
	v_sub_u32_e32 v2, 0x86, v0
	v_sub_u32_e32 v0, 0x87, v0
	v_cvt_f32_ubyte0_e32 v74, v0
	v_or_b32_e32 v0, 0x80, v82
	v_cvt_f32_ubyte0_e32 v73, v2
	s_movk_i32 s20, 0x88
	v_sub_u32_e32 v2, 0x81, v0
	s_movk_i32 s36, 0x80
	v_cmp_gt_u32_e64 s[20:21], s20, v0
	v_cmp_gt_u32_e32 vcc, s36, v2
	v_cvt_f32_u32_e32 v75, v2
	v_sub_u32_e32 v2, 0x82, v0
	s_and_b64 s[22:23], s[20:21], vcc
	v_cmp_gt_u32_e32 vcc, s36, v2
	v_cvt_f32_u32_e32 v76, v2
	v_sub_u32_e32 v2, 0x83, v0
	s_and_b64 s[24:25], s[20:21], vcc
	v_cmp_gt_u32_e32 vcc, s36, v2
	v_cvt_f32_u32_e32 v77, v2
	v_sub_u32_e32 v2, 0x84, v0
	s_and_b64 s[26:27], s[20:21], vcc
	v_cmp_gt_u32_e32 vcc, s36, v2
	v_cvt_f32_u32_e32 v78, v2
	v_sub_u32_e32 v2, 0x85, v0
	s_and_b64 s[28:29], s[20:21], vcc
	v_cmp_gt_u32_e32 vcc, s36, v2
	v_cvt_f32_u32_e32 v79, v2
	v_sub_u32_e32 v2, 0x86, v0
	s_mulk_i32 s44, 0x3000
	s_and_b64 s[30:31], s[20:21], vcc
	v_cmp_gt_u32_e32 vcc, s36, v2
	v_sub_u32_e32 v0, 0x87, v0
	s_add_i32 s55, s44, 0
	s_and_b64 s[34:35], s[20:21], vcc
	v_cmp_gt_u32_e32 vcc, s36, v0
	v_readlane_b32 s44, v255, 0
	s_and_b64 s[36:37], s[20:21], vcc
	s_and_b32 s44, s44, 0xc0
	s_cmp_eq_u32 s44, 0
	v_readlane_b32 s46, v254, 58
	s_cselect_b64 s[44:45], -1, 0
	v_readlane_b32 s47, v254, 59
	s_add_u32 s46, s46, s42
	v_cvt_f32_u32_e32 v81, v0
	s_addc_u32 s47, s47, s43
	v_lshlrev_b32_e32 v0, 9, v82
	v_cvt_f32_u32_e32 v80, v2
	v_lshl_add_u64 v[2:3], s[46:47], 0, v[0:1]
	s_mov_b64 s[48:49], 0x8040
	v_lshl_add_u64 v[34:35], v[2:3], 0, s[48:49]
	v_readlane_b32 s48, v255, 3
	v_readlane_b32 s49, v255, 4
	s_add_u32 s56, s48, 0x19208810
	s_addc_u32 s57, s49, 0
	s_add_i32 s62, s55, 0x800
	v_readlane_b32 s48, v254, 60
	v_readlane_b32 s49, v254, 61
	s_add_u32 s48, s48, s42
	v_mov_b32_e32 v83, v1
	v_lshlrev_b32_e32 v0, 2, v82
	s_addc_u32 s49, s49, s43
	v_lshlrev_b64 v[28:29], 1, v[82:83]
	v_lshlrev_b32_e32 v4, 5, v82
	v_lshl_add_u64 v[2:3], s[48:49], 0, v[0:1]
	s_mov_b64 s[48:49], 0x1000
	v_lshl_add_u64 v[30:31], s[96:97], 0, v[28:29]
	v_lshl_add_u32 v58, v82, 2, s55
	v_lshlrev_b32_e32 v26, 1, v82
	v_mov_b32_e32 v27, v1
	v_cmp_eq_u32_e64 s[4:5], 0, v82
	v_cmp_lt_u32_e64 s[6:7], 1, v82
	v_cmp_lt_u32_e64 s[8:9], 2, v82
	v_cmp_lt_u32_e64 s[10:11], 3, v82
	v_cmp_lt_u32_e64 s[12:13], 4, v82
	v_cmp_lt_u32_e64 s[14:15], 5, v82
	v_cmp_lt_u32_e64 s[16:17], 6, v82
	v_cmp_lt_u32_e64 s[18:19], 7, v82
	v_cmp_gt_u32_e64 s[38:39], 8, v82
	v_lshl_add_u64 v[32:33], s[92:93], 0, v[28:29]
	v_lshl_add_u64 v[36:37], v[2:3], 0, s[48:49]
	v_add_u32_e32 v0, s55, v4
	s_mov_b32 s63, s54
	s_cmpk_lg_i32 s88, 0x100
	s_cbranch_scc1 .LBB0_1063
	s_lshr_b32 s4, s54, 3
	s_and_b32 s5, s54, 7
	s_lshr_b32 s6, s4, 3
	s_and_b32 s7, s4, 7
	s_lshl_b32 s8, s7, 1
	s_lshr_b32 s9, s7, 2
	v_readlane_b32 s10, v254, 42
	v_readlane_b32 s11, v254, 43
	v_readlane_b32 s16, v254, 58
	v_readlane_b32 s17, v254, 59
	v_readlane_b32 s18, v254, 60
	v_readlane_b32 s19, v254, 61
	s_add_u32 s12, s10, 0x13e08000
	s_addc_u32 s13, s11, 0
	s_add_u32 s14, s10, 0x20408000
	s_addc_u32 s15, s11, 0
	s_mul_i32 s20, s6, 0x15000
	s_add_u32 s20, s20, 0x5400000
	s_add_u32 s12, s12, s20
	s_addc_u32 s13, s13, 0
	s_lshl_b32 s21, s8, 7
	s_add_u32 s22, s12, s21
	s_addc_u32 s23, s13, 0
	v_lshrrev_b32_e32 v54, 5, v139
	v_and_b32_e32 v55, 7, v54
	v_lshrrev_b32_e32 v56, 3, v54
	v_mul_u32_u24_e32 v57, 0x2a00, v55
	v_lshl_add_u32 v57, v56, 7, v57
	v_and_b32_e32 v83, 31, v139
	v_lshl_add_u32 v57, v83, 2, v57
	global_load_dword v170, v57, s[22:23]
	s_lshl_b32 s24, s6, 16
	s_lshl_b32 s25, s5, 13
	s_add_i32 s24, s24, s25
	s_lshl_b32 s25, s9, 8
	s_add_i32 s28, s24, s25
	s_add_u32 s16, s16, s42
	s_addc_u32 s17, s17, s43
	s_add_u32 s24, s16, s28
	s_addc_u32 s25, s17, 0
	s_add_u32 s18, s18, s42
	s_addc_u32 s19, s19, s43
	s_add_u32 s26, s18, s28
	s_addc_u32 s27, s19, 0
	v_and_b32_e32 v125, 15, v215
	v_lshrrev_b32_e32 v134, 4, v215
	v_lshlrev_b32_e32 v135, 9, v125
	v_lshl_add_u32 v135, v134, 4, v135
	global_load_dwordx4 v[84:87], v135, s[24:25] offset:0
	global_load_dwordx4 v[88:91], v135, s[24:25] offset:64
	global_load_dwordx4 v[92:95], v135, s[24:25] offset:128
	global_load_dwordx4 v[96:99], v135, s[24:25] offset:192
	s_lshl_b32 s28, s9, 7
	s_addk_i32 s28, 0x800
	s_add_u32 s28, s12, s28
	s_addc_u32 s29, s13, 0
	v_and_b32_e32 v136, 7, v125
	v_mul_u32_u24_e32 v136, 0x2a00, v136
	v_lshl_add_u32 v136, v134, 3, v136
	global_load_dwordx2 v[100:101], v136, s[28:29] offset:0
	global_load_dwordx2 v[102:103], v136, s[28:29] offset:32
	global_load_dwordx2 v[104:105], v136, s[28:29] offset:64
	global_load_dwordx2 v[106:107], v136, s[28:29] offset:96
	v_lshlrev_b32_e32 v146, 11, v134
	v_lshl_add_u32 v146, v125, 4, v146
	global_load_dwordx4 v[2:5], v146, s[26:27] offset:0
	global_load_dwordx4 v[6:9], v146, s[26:27] offset:512
	global_load_dwordx4 v[10:13], v146, s[26:27] offset:1024
	global_load_dwordx4 v[14:17], v146, s[26:27] offset:1536
	v_and_b32_e32 v148, 1, v134
	v_mul_u32_u24_e32 v148, 0xa800, v148
	v_lshl_add_u32 v148, v125, 3, v148
	s_add_u32 s30, s28, 0x100
	s_addc_u32 s31, s29, 0
	global_load_dwordx2 v[18:19], v148, s[30:31]
	s_add_u32 s30, s30, 0x2a00
	s_addc_u32 s31, s31, 0
	global_load_dwordx2 v[20:21], v148, s[30:31]
	s_add_u32 s30, s30, 0x2a00
	s_addc_u32 s31, s31, 0
	global_load_dwordx2 v[22:23], v148, s[30:31]
	s_add_u32 s30, s30, 0x2a00
	s_addc_u32 s31, s31, 0
	global_load_dwordx2 v[24:25], v148, s[30:31]
	global_load_dword v171, v57, s[22:23] offset:2560
	s_lshl_b32 s30, s8, 2
	s_add_u32 s30, s40, s30
	s_addc_u32 s31, s41, 0
	s_load_dwordx2 s[34:35], s[30:31], 0x0
	v_mul_u32_u24_e32 v149, 272, v54
	v_lshl_add_u32 v149, v83, 3, v149
	s_waitcnt vmcnt(17)
	v_lshlrev_b32_e32 v150, 16, v170
	v_and_b32_e32 v151, 0xffff0000, v170
	ds_write_b64 v149, v[150:151]
	s_waitcnt lgkmcnt(0)
	s_barrier
; #define LAS __attribute__((address_space(3)))
; __device__ __forceinline__ float bf_lo(unsigned w) { return __uint_as_float(w << 16); }
; __device__ __forceinline__ float bf_hi(unsigned w) { return __uint_as_float(w & 0xffff0000u); }
; __device__ __forceinline__ void attn_sample_item(LAS float* wl, const bf16_t* z, bf16_t* mix, const float* sinks, const float* ck, const float* cv, int it, int lane) {
;     ...
;     float s[3][8];
; #pragma unroll
;     for (int ps = 0; ps < 3; ++ps) {
;         const int idx = lane + 64 * ps;
; #pragma unroll
;         for (int t = 0; t < 8; ++t) s[ps][t] = 0.f;
;         if (idx < 128) {
;             const f32x4* kp = (const f32x4*)(ck + (((size_t)b * 128 + idx) * 2 + kv) * 64);
; #pragma unroll 8
;             for (int d4 = 0; d4 < 16; ++d4) {
;                 const f32x4 k4 = kp[d4];
; #pragma unroll
;                 for (int t = 0; t < 8; ++t) { const f32x4 q4 = *(const LAS f32x4*)(qs + t * 64 + 4 * d4); s[ps][t] += (k4[0] * q4[0] + k4[1] * q4[1]) + (k4[2] * q4[2] + k4[3] * q4[3]); }
;             }
;         } else if (idx < 136) {
;             const bf16_t* kp = z + (tok0 + (idx - 128)) * EIN + 1024 + kv * 64;
; #pragma unroll 4
;             for (int d4 = 0; d4 < 16; ++d4) {
;                 const u32x2 kw = *(const u32x2*)(kp + 4 * d4);
;                 const float k0 = bf_lo(kw.x), k1 = bf_hi(kw.x), k2 = bf_lo(kw.y), k3 = bf_hi(kw.y);
; #pragma unroll
;                 for (int t = 0; t < 8; ++t) { const f32x4 q4 = *(const LAS f32x4*)(qs + t * 64 + 4 * d4); s[ps][t] += (k0 * q4[0] + k1 * q4[1]) + (k2 * q4[2] + k3 * q4[3]); }
;             }
;         }
; #pragma unroll
;         for (int t = 0; t < 8; ++t) {
;             const int dist = t + 128 - idx;
;             const bool valid = (idx < 136) && (dist >= 0) && (dist < 128);
;             s[ps][t] = valid ? s[ps][t] * 0.125f - slope * (float)dist : -1e30f;
;         }
;     }
	v_mul_u32_u24_e32 v149, 272, v125
	v_lshl_add_u32 v149, v134, 4, v149
	ds_read_b128 v[154:157], v149 offset:0
	ds_read_b128 v[158:161], v149 offset:64
	ds_read_b128 v[162:165], v149 offset:128
	ds_read_b128 v[166:169], v149 offset:192
	v_lshrrev_b32_e32 v150, 3, v125
	v_add_u32_e32 v150, s8, v150
	v_add_u32_e32 v150, 1, v150
	v_cvt_f32_u32_e32 v150, v150
	v_mul_f32_e32 v150, -0.5, v150
	v_exp_f32_e32 v150, v150
	v_and_b32_e32 v151, 7, v125
	v_lshlrev_b32_e32 v55, 2, v134
	v_sub_u32_e32 v56, v151, v55
	s_lshl_b32 s30, s5, 4
	s_sub_i32 s30, 0x80, s30
	v_add_u32_e32 v55, s30, v56
	v_cmp_gt_u32_e64 s[38:39], 32, v215
	s_cmp_eq_u32 s5, 0
	s_cselect_b64 s[36:37], -1, 0
	s_and_b64 s[38:39], s[38:39], s[36:37]
	s_waitcnt vmcnt(13) lgkmcnt(0)
	v_mfma_f32_16x16x4_f32 v[126:129], v84, v154, 0
	v_mfma_f32_16x16x4_f32 v[126:129], v85, v155, v[126:129]
	v_mfma_f32_16x16x4_f32 v[126:129], v86, v156, v[126:129]
	v_mfma_f32_16x16x4_f32 v[126:129], v87, v157, v[126:129]
	v_mfma_f32_16x16x4_f32 v[126:129], v88, v158, v[126:129]
	v_mfma_f32_16x16x4_f32 v[126:129], v89, v159, v[126:129]
	v_mfma_f32_16x16x4_f32 v[126:129], v90, v160, v[126:129]
	v_mfma_f32_16x16x4_f32 v[126:129], v91, v161, v[126:129]
	v_mfma_f32_16x16x4_f32 v[126:129], v92, v162, v[126:129]
	v_mfma_f32_16x16x4_f32 v[126:129], v93, v163, v[126:129]
	v_mfma_f32_16x16x4_f32 v[126:129], v94, v164, v[126:129]
	v_mfma_f32_16x16x4_f32 v[126:129], v95, v165, v[126:129]
	v_mfma_f32_16x16x4_f32 v[126:129], v96, v166, v[126:129]
	v_mfma_f32_16x16x4_f32 v[126:129], v97, v167, v[126:129]
	v_mfma_f32_16x16x4_f32 v[126:129], v98, v168, v[126:129]
	v_mfma_f32_16x16x4_f32 v[126:129], v99, v169, v[126:129]
	s_cmp_lg_u32 s5, 0
	s_cbranch_scc1 .Lsa_noselfqk
	s_waitcnt vmcnt(9)
	v_lshlrev_b32_e32 v108, 16, v100
	v_and_b32_e32 v109, 0xffff0000, v100
	v_lshlrev_b32_e32 v110, 16, v101
	v_and_b32_e32 v111, 0xffff0000, v101
	v_lshlrev_b32_e32 v112, 16, v102
	v_and_b32_e32 v113, 0xffff0000, v102
	v_lshlrev_b32_e32 v114, 16, v103
	v_and_b32_e32 v115, 0xffff0000, v103
	v_lshlrev_b32_e32 v116, 16, v104
	v_and_b32_e32 v117, 0xffff0000, v104
	v_lshlrev_b32_e32 v118, 16, v105
	v_and_b32_e32 v119, 0xffff0000, v105
	v_lshlrev_b32_e32 v120, 16, v106
	v_and_b32_e32 v121, 0xffff0000, v106
	v_lshlrev_b32_e32 v122, 16, v107
	v_and_b32_e32 v123, 0xffff0000, v107
	s_nop 1
	v_mfma_f32_16x16x4_f32 v[130:133], v108, v154, 0
	v_mfma_f32_16x16x4_f32 v[130:133], v109, v155, v[130:133]
	v_mfma_f32_16x16x4_f32 v[130:133], v110, v156, v[130:133]
	v_mfma_f32_16x16x4_f32 v[130:133], v111, v157, v[130:133]
	v_mfma_f32_16x16x4_f32 v[130:133], v112, v158, v[130:133]
	v_mfma_f32_16x16x4_f32 v[130:133], v113, v159, v[130:133]
	v_mfma_f32_16x16x4_f32 v[130:133], v114, v160, v[130:133]
	v_mfma_f32_16x16x4_f32 v[130:133], v115, v161, v[130:133]
	v_mfma_f32_16x16x4_f32 v[130:133], v116, v162, v[130:133]
	v_mfma_f32_16x16x4_f32 v[130:133], v117, v163, v[130:133]
	v_mfma_f32_16x16x4_f32 v[130:133], v118, v164, v[130:133]
	v_mfma_f32_16x16x4_f32 v[130:133], v119, v165, v[130:133]
	v_mfma_f32_16x16x4_f32 v[130:133], v120, v166, v[130:133]
	v_mfma_f32_16x16x4_f32 v[130:133], v121, v167, v[130:133]
	v_mfma_f32_16x16x4_f32 v[130:133], v122, v168, v[130:133]
	v_mfma_f32_16x16x4_f32 v[130:133], v123, v169, v[130:133]
.Lsa_noselfqk:
	s_nop 7
	s_nop 7
	v_subrev_u32_e32 v57, 0, v55
	v_cvt_f32_i32_e32 v83, v57
	v_mul_f32_e32 v126, v144, v126
	v_cmp_gt_i32_e32 vcc, 0x80, v57
	v_fma_f32 v126, -v150, v83, v126
	v_cndmask_b32_e32 v126, v221, v126, vcc
	v_subrev_u32_e32 v57, 1, v55
	v_cvt_f32_i32_e32 v83, v57
	v_mul_f32_e32 v127, v144, v127
	v_cmp_gt_i32_e32 vcc, 0x80, v57
	v_fma_f32 v127, -v150, v83, v127
	v_cndmask_b32_e32 v127, v221, v127, vcc
	v_subrev_u32_e32 v57, 2, v55
	v_cvt_f32_i32_e32 v83, v57
	v_mul_f32_e32 v128, v144, v128
	v_cmp_gt_i32_e32 vcc, 0x80, v57
	v_fma_f32 v128, -v150, v83, v128
	v_cndmask_b32_e32 v128, v221, v128, vcc
	v_subrev_u32_e32 v57, 3, v55
	v_cvt_f32_i32_e32 v83, v57
	v_mul_f32_e32 v129, v144, v129
	v_cmp_gt_i32_e32 vcc, 0x80, v57
	v_fma_f32 v129, -v150, v83, v129
	v_cndmask_b32_e32 v129, v221, v129, vcc
	v_subrev_u32_e32 v57, 0, v56
	v_cvt_f32_i32_e32 v83, v57
	v_mul_f32_e32 v130, v144, v130
	v_cmp_le_i32_e32 vcc, 0, v57
	v_fma_f32 v130, -v150, v83, v130
	s_and_b64 vcc, vcc, s[38:39]
	v_cndmask_b32_e32 v130, v221, v130, vcc
	v_subrev_u32_e32 v57, 1, v56
	v_cvt_f32_i32_e32 v83, v57
	v_mul_f32_e32 v131, v144, v131
	v_cmp_le_i32_e32 vcc, 0, v57
	v_fma_f32 v131, -v150, v83, v131
	s_and_b64 vcc, vcc, s[38:39]
	v_cndmask_b32_e32 v131, v221, v131, vcc
	v_subrev_u32_e32 v57, 2, v56
	v_cvt_f32_i32_e32 v83, v57
	v_mul_f32_e32 v132, v144, v132
	v_cmp_le_i32_e32 vcc, 0, v57
	v_fma_f32 v132, -v150, v83, v132
	s_and_b64 vcc, vcc, s[38:39]
	v_cndmask_b32_e32 v132, v221, v132, vcc
	v_subrev_u32_e32 v57, 3, v56
	v_cvt_f32_i32_e32 v83, v57
	v_mul_f32_e32 v133, v144, v133
	v_cmp_le_i32_e32 vcc, 0, v57
	v_fma_f32 v133, -v150, v83, v133
	s_and_b64 vcc, vcc, s[38:39]
	v_cndmask_b32_e32 v133, v221, v133, vcc
	v_xor_b32_e32 v54, 16, v215
	v_lshlrev_b32_e32 v54, 2, v54
	v_xor_b32_e32 v57, 32, v215
	v_lshlrev_b32_e32 v57, 2, v57
	v_max3_f32 v148, v126, v127, v128
	v_max3_f32 v148, v148, v129, v130
	v_max3_f32 v148, v148, v131, v132
	v_max_f32_e32 v148, v148, v133
	ds_bpermute_b32 v83, v54, v148
	s_waitcnt lgkmcnt(0)
	v_max_f32_e32 v148, v148, v83
	ds_bpermute_b32 v83, v57, v148
	s_waitcnt lgkmcnt(0)
; #define LAS __attribute__((address_space(3)))
; __device__ __forceinline__ void attn_sample_item(LAS float* wl, const bf16_t* z, bf16_t* mix, const float* sinks, const float* ck, const float* cv, int it, int lane) {
;     ...
; #pragma unroll
;     for (int t = 0; t < 8; ++t) {
;         float m = fmaxf(fmaxf(s[0][t], s[1][t]), s[2][t]); m = fmaxf(wave_max(m), sink);
;         const float p0 = __expf(s[0][t] - m), p1 = __expf(s[1][t] - m), p2 = __expf(s[2][t] - m);
;         const float den = wave_sum(p0 + p1 + p2) + __expf(sink - m), inv = 1.0f / den;
;         pT[lane * 8 + t] = p0 * inv; pT[(lane + 64) * 8 + t] = p1 * inv; if (lane < 8) pT[(lane + 128) * 8 + t] = p2 * inv;
;     }
;     __builtin_amdgcn_wave_barrier();
;     asm volatile("s_waitcnt lgkmcnt(0)" ::: "memory");
;     float o[8];
; #pragma unroll
;     for (int t = 0; t < 8; ++t) o[t] = 0.f;
;     for (int i0 = 0; i0 < 128; i0 += 16) {
;         float vv[16];
; #pragma unroll
;         for (int j = 0; j < 16; ++j) vv[j] = cv[(((size_t)b * 128 + i0 + j) * 2 + kv) * 64 + lane];
; #pragma unroll
;         for (int j = 0; j < 16; ++j) {
;         const int idx = i0 + j; const float v = vv[j];
;         const f32x4 pa = *(const LAS f32x4*)(pT + idx * 8), pb = *(const LAS f32x4*)(pT + idx * 8 + 4);
;         o[0] += pa[0] * v; o[1] += pa[1] * v; o[2] += pa[2] * v; o[3] += pa[3] * v; o[4] += pb[0] * v; o[5] += pb[1] * v; o[6] += pb[2] * v; o[7] += pb[3] * v;
	v_max_f32_e32 v148, v148, v83
	v_mov_b32_e32 v149, 0
	v_sub_f32_e32 v126, v126, v148
	v_mul_f32_e32 v126, 0x3fb8aa3b, v126
	v_exp_f32_e32 v126, v126
	v_sub_f32_e32 v127, v127, v148
	v_mul_f32_e32 v127, 0x3fb8aa3b, v127
	v_exp_f32_e32 v127, v127
	v_add_f32_e32 v149, v126, v149
	v_sub_f32_e32 v128, v128, v148
	v_mul_f32_e32 v128, 0x3fb8aa3b, v128
	v_exp_f32_e32 v128, v128
	v_add_f32_e32 v149, v127, v149
	v_sub_f32_e32 v129, v129, v148
	v_mul_f32_e32 v129, 0x3fb8aa3b, v129
	v_exp_f32_e32 v129, v129
	v_add_f32_e32 v149, v128, v149
	v_sub_f32_e32 v130, v130, v148
	v_mul_f32_e32 v130, 0x3fb8aa3b, v130
	v_exp_f32_e32 v130, v130
	v_add_f32_e32 v149, v129, v149
	v_sub_f32_e32 v131, v131, v148
	v_mul_f32_e32 v131, 0x3fb8aa3b, v131
	v_exp_f32_e32 v131, v131
	v_add_f32_e32 v149, v130, v149
	v_sub_f32_e32 v132, v132, v148
	v_mul_f32_e32 v132, 0x3fb8aa3b, v132
	v_exp_f32_e32 v132, v132
	v_add_f32_e32 v149, v131, v149
	v_sub_f32_e32 v133, v133, v148
	v_mul_f32_e32 v133, 0x3fb8aa3b, v133
	v_exp_f32_e32 v133, v133
	v_add_f32_e32 v149, v132, v149
	s_nop 0
	v_add_f32_e32 v149, v133, v149
	ds_bpermute_b32 v83, v54, v149
	s_waitcnt lgkmcnt(0)
	v_add_f32_e32 v149, v149, v83
	ds_bpermute_b32 v83, v57, v149
	s_waitcnt lgkmcnt(0)
	v_add_f32_e32 v149, v149, v83
	v_cmp_gt_u32_e32 vcc, 16, v215
	s_lshl_b32 s30, s5, 7
	v_lshl_add_u32 v83, v215, 3, s30
	v_add_u32_e32 v83, 0x1200, v83
	s_and_saveexec_b64 s[36:37], vcc
	ds_write_b64 v83, v[148:149]
	s_or_b64 exec, exec, s[36:37]
	s_waitcnt vmcnt(5)
	v_mfma_f32_16x16x4_f32 v[84:87], v126, v2, 0
	v_mfma_f32_16x16x4_f32 v[88:91], v126, v3, 0
	v_mfma_f32_16x16x4_f32 v[92:95], v126, v4, 0
	v_mfma_f32_16x16x4_f32 v[96:99], v126, v5, 0
	v_mfma_f32_16x16x4_f32 v[84:87], v127, v6, v[84:87]
	v_mfma_f32_16x16x4_f32 v[88:91], v127, v7, v[88:91]
	v_mfma_f32_16x16x4_f32 v[92:95], v127, v8, v[92:95]
	v_mfma_f32_16x16x4_f32 v[96:99], v127, v9, v[96:99]
	v_mfma_f32_16x16x4_f32 v[84:87], v128, v10, v[84:87]
	v_mfma_f32_16x16x4_f32 v[88:91], v128, v11, v[88:91]
	v_mfma_f32_16x16x4_f32 v[92:95], v128, v12, v[92:95]
	v_mfma_f32_16x16x4_f32 v[96:99], v128, v13, v[96:99]
	v_mfma_f32_16x16x4_f32 v[84:87], v129, v14, v[84:87]
	v_mfma_f32_16x16x4_f32 v[88:91], v129, v15, v[88:91]
	v_mfma_f32_16x16x4_f32 v[92:95], v129, v16, v[92:95]
	v_mfma_f32_16x16x4_f32 v[96:99], v129, v17, v[96:99]
	s_cmp_lg_u32 s5, 0
	s_cbranch_scc1 .Lsa_noselfpv
	s_waitcnt vmcnt(1)
	v_lshlrev_b32_e32 v38, 16, v18
	v_and_b32_e32 v39, 0xffff0000, v18
	v_lshlrev_b32_e32 v40, 16, v19
	v_and_b32_e32 v41, 0xffff0000, v19
	v_lshlrev_b32_e32 v42, 16, v20
	v_and_b32_e32 v43, 0xffff0000, v20
	v_lshlrev_b32_e32 v44, 16, v21
	v_and_b32_e32 v45, 0xffff0000, v21
	v_lshlrev_b32_e32 v46, 16, v22
	v_and_b32_e32 v47, 0xffff0000, v22
	v_lshlrev_b32_e32 v48, 16, v23
	v_and_b32_e32 v49, 0xffff0000, v23
	v_lshlrev_b32_e32 v50, 16, v24
	v_and_b32_e32 v51, 0xffff0000, v24
	v_lshlrev_b32_e32 v52, 16, v25
	v_and_b32_e32 v53, 0xffff0000, v25
	s_nop 1
	v_mfma_f32_16x16x4_f32 v[84:87], v130, v38, v[84:87]
	v_mfma_f32_16x16x4_f32 v[88:91], v130, v39, v[88:91]
	v_mfma_f32_16x16x4_f32 v[92:95], v130, v40, v[92:95]
	v_mfma_f32_16x16x4_f32 v[96:99], v130, v41, v[96:99]
	v_mfma_f32_16x16x4_f32 v[84:87], v131, v42, v[84:87]
	v_mfma_f32_16x16x4_f32 v[88:91], v131, v43, v[88:91]
	v_mfma_f32_16x16x4_f32 v[92:95], v131, v44, v[92:95]
	v_mfma_f32_16x16x4_f32 v[96:99], v131, v45, v[96:99]
	v_mfma_f32_16x16x4_f32 v[84:87], v132, v46, v[84:87]
	v_mfma_f32_16x16x4_f32 v[88:91], v132, v47, v[88:91]
	v_mfma_f32_16x16x4_f32 v[92:95], v132, v48, v[92:95]
	v_mfma_f32_16x16x4_f32 v[96:99], v132, v49, v[96:99]
	v_mfma_f32_16x16x4_f32 v[84:87], v133, v50, v[84:87]
	v_mfma_f32_16x16x4_f32 v[88:91], v133, v51, v[88:91]
	v_mfma_f32_16x16x4_f32 v[92:95], v133, v52, v[92:95]
	v_mfma_f32_16x16x4_f32 v[96:99], v133, v53, v[96:99]
; __device__ __forceinline__ float bf1(bf16_t h) { return __uint_as_float((unsigned)h << 16); }
; __device__ __forceinline__ bf16_t f2bf(float f) { return (bf16_t)(pk2(f, 0.f) & 0xffffu); }
; __device__ __forceinline__ void attn_sample_item(LAS float* wl, const bf16_t* z, bf16_t* mix, const float* sinks, const float* ck, const float* cv, int it, int lane) {
;     ...
;     for (int t = 0; t < 8; ++t) {
;         float m = fmaxf(fmaxf(s[0][t], s[1][t]), s[2][t]); m = fmaxf(wave_max(m), sink);
;         const float p0 = __expf(s[0][t] - m), p1 = __expf(s[1][t] - m), p2 = __expf(s[2][t] - m);
;         const float den = wave_sum(p0 + p1 + p2) + __expf(sink - m), inv = 1.0f / den;
;         pT[lane * 8 + t] = p0 * inv; pT[(lane + 64) * 8 + t] = p1 * inv; if (lane < 8) pT[(lane + 128) * 8 + t] = p2 * inv;
;     }
;     ...
; #pragma unroll
;     for (int t = 0; t < 8; ++t) {
;         const float ga = bf1(z[(tok0 + t) * EIN + 1280 + h * 64 + lane]);
;         mix[(tok0 + t) * 2048 + h * 64 + lane] = f2bf(o[t] * ga);
;     }
.Lsa_noselfpv:
	s_nop 7
	s_nop 7
	s_lshl_b32 s30, s5, 12
	v_lshl_add_u32 v83, v215, 4, s30
	v_add_u32_e32 v83, 0x2000, v83
	ds_write_b128 v83, v[84:87] offset:0
	ds_write_b128 v83, v[88:91] offset:1024
	ds_write_b128 v83, v[92:95] offset:2048
	ds_write_b128 v83, v[96:99] offset:3072
	s_waitcnt lgkmcnt(0)
	s_barrier
	v_lshrrev_b32_e32 v54, 5, v139
	v_and_b32_e32 v55, 31, v139
	v_lshlrev_b32_e32 v56, 3, v54
	v_add_u32_e32 v56, 0x1200, v56
	ds_read_b64 v[2:3], v56 offset:0
	ds_read_b64 v[4:5], v56 offset:128
	ds_read_b64 v[6:7], v56 offset:256
	ds_read_b64 v[8:9], v56 offset:384
	ds_read_b64 v[10:11], v56 offset:512
	ds_read_b64 v[12:13], v56 offset:640
	ds_read_b64 v[14:15], v56 offset:768
	ds_read_b64 v[16:17], v56 offset:896
	v_and_b32_e32 v57, 1, v55
	v_lshlrev_b32_e32 v57, 11, v57
	v_lshrrev_b32_e32 v83, 1, v55
	v_lshrrev_b32_e32 v125, 2, v54
	v_lshl_add_u32 v83, v125, 4, v83
	v_lshl_add_u32 v57, v83, 4, v57
	v_and_b32_e32 v83, 3, v54
	v_lshl_add_u32 v57, v83, 2, v57
	v_add_u32_e32 v57, 0x2000, v57
	ds_read_b32 v38, v57 offset:0
	ds_read_b32 v39, v57 offset:1024
	ds_read_b32 v40, v57 offset:4096
	ds_read_b32 v41, v57 offset:5120
	ds_read_b32 v42, v57 offset:8192
	ds_read_b32 v43, v57 offset:9216
	ds_read_b32 v44, v57 offset:12288
	ds_read_b32 v45, v57 offset:13312
	ds_read_b32 v46, v57 offset:16384
	ds_read_b32 v47, v57 offset:17408
	ds_read_b32 v48, v57 offset:20480
	ds_read_b32 v49, v57 offset:21504
	ds_read_b32 v50, v57 offset:24576
	ds_read_b32 v51, v57 offset:25600
	ds_read_b32 v52, v57 offset:28672
	ds_read_b32 v53, v57 offset:29696
	s_cmp_lt_u32 s5, 4
	s_waitcnt lgkmcnt(0)
	s_cselect_b32 s30, s34, s35
	v_mov_b32_e32 v83, s30
	v_max3_f32 v84, v2, v4, v6
	v_max3_f32 v84, v84, v8, v10
	v_max3_f32 v84, v84, v12, v14
	v_max3_f32 v84, v84, v16, v83
	v_sub_f32_e32 v85, v83, v84
	v_mul_f32_e32 v85, 0x3fb8aa3b, v85
	v_exp_f32_e32 v85, v85
	v_mov_b32_e32 v86, 0
	v_mov_b32_e32 v87, 0
	v_sub_f32_e32 v88, v2, v84
	v_mul_f32_e32 v88, 0x3fb8aa3b, v88
	v_exp_f32_e32 v88, v88
	s_nop 0
	v_fmac_f32_e32 v85, v88, v3
	v_fmac_f32_e32 v86, v88, v38
	v_fmac_f32_e32 v87, v88, v39
	v_sub_f32_e32 v88, v4, v84
	v_mul_f32_e32 v88, 0x3fb8aa3b, v88
	v_exp_f32_e32 v88, v88
	s_nop 0
	v_fmac_f32_e32 v85, v88, v5
	v_fmac_f32_e32 v86, v88, v40
	v_fmac_f32_e32 v87, v88, v41
	v_sub_f32_e32 v88, v6, v84
	v_mul_f32_e32 v88, 0x3fb8aa3b, v88
	v_exp_f32_e32 v88, v88
	s_nop 0
	v_fmac_f32_e32 v85, v88, v7
	v_fmac_f32_e32 v86, v88, v42
	v_fmac_f32_e32 v87, v88, v43
	v_sub_f32_e32 v88, v8, v84
	v_mul_f32_e32 v88, 0x3fb8aa3b, v88
	v_exp_f32_e32 v88, v88
	s_nop 0
	v_fmac_f32_e32 v85, v88, v9
	v_fmac_f32_e32 v86, v88, v44
	v_fmac_f32_e32 v87, v88, v45
	v_sub_f32_e32 v88, v10, v84
	v_mul_f32_e32 v88, 0x3fb8aa3b, v88
	v_exp_f32_e32 v88, v88
	s_nop 0
	v_fmac_f32_e32 v85, v88, v11
	v_fmac_f32_e32 v86, v88, v46
	v_fmac_f32_e32 v87, v88, v47
	v_sub_f32_e32 v88, v12, v84
	v_mul_f32_e32 v88, 0x3fb8aa3b, v88
	v_exp_f32_e32 v88, v88
	s_nop 0
	v_fmac_f32_e32 v85, v88, v13
	v_fmac_f32_e32 v86, v88, v48
	v_fmac_f32_e32 v87, v88, v49
	v_sub_f32_e32 v88, v14, v84
	v_mul_f32_e32 v88, 0x3fb8aa3b, v88
	v_exp_f32_e32 v88, v88
	s_nop 0
	v_fmac_f32_e32 v85, v88, v15
	v_fmac_f32_e32 v86, v88, v50
	v_fmac_f32_e32 v87, v88, v51
	v_sub_f32_e32 v88, v16, v84
	v_mul_f32_e32 v88, 0x3fb8aa3b, v88
	v_exp_f32_e32 v88, v88
	s_nop 0
	v_fmac_f32_e32 v85, v88, v17
	v_fmac_f32_e32 v86, v88, v52
	v_fmac_f32_e32 v87, v88, v53
	v_div_scale_f32 v88, s[36:37], v85, v85, 1.0
	v_rcp_f32_e32 v89, v88
	s_nop 0
	v_fma_f32 v90, -v88, v89, 1.0
	v_fmac_f32_e32 v89, v90, v89
	v_div_scale_f32 v90, vcc, 1.0, v85, 1.0
	v_mul_f32_e32 v91, v90, v89
	v_fma_f32 v92, -v88, v91, v90
	v_fmac_f32_e32 v91, v92, v89
	v_fma_f32 v88, -v88, v91, v90
	v_div_fmas_f32 v88, v88, v89, v91
	v_div_fixup_f32 v88, v88, v85, 1.0
	v_mul_f32_e32 v86, v86, v88
	v_mul_f32_e32 v87, v87, v88
	s_waitcnt vmcnt(0)
	v_lshlrev_b32_e32 v89, 16, v171
	v_and_b32_e32 v90, 0xffff0000, v171
	v_mul_f32_e32 v86, v86, v89
	v_mul_f32_e32 v87, v87, v90
	v_cvt_pk_bf16_f32 v86, v86, v87
	s_lshl_b32 s30, s6, 3
	s_addk_i32 s30, 0x2000
	s_lshl_b32 s30, s30, 12
	s_add_i32 s30, s30, s21
	s_add_u32 s14, s14, s30
	s_addc_u32 s15, s15, 0
	v_and_b32_e32 v89, 7, v54
	v_lshrrev_b32_e32 v90, 3, v54
	v_lshlrev_b32_e32 v89, 12, v89
	v_lshl_add_u32 v89, v90, 7, v89
	v_lshl_add_u32 v89, v55, 2, v89
	global_store_dword v89, v86, s[14:15]
	s_branch .LBB0_1062
